# GEMM K-loops: 8 of 16 LDS-DMA pieces per iteration now use saddr+voffset addressing (v_lshl_add_u64 address adds deleted from the load segments)
# baseline (speedup 1.0000x reference)
.LBB0_169:
	s_add_u32 s42, s40, 0xfff80080
	s_addc_u32 s43, s41, -1
	s_add_i32 s52, 0, 0x10000
	s_cmp_eq_u32 s51, 28
	s_cselect_b32 s45, s13, s43
	s_cselect_b32 s44, s47, s42
	s_cselect_b32 s43, s11, s50
	s_cselect_b32 s42, s48, s49
	s_add_i32 s54, 0, 0x14000
	v_add_u32_e32 v142, s52, v175
	v_add_u32_e32 v154, s54, v175
	ds_read_b128 v[130:133], v142
	ds_read_b128 v[134:137], v142 offset:1024
	ds_read_b128 v[138:141], v142 offset:2048
	ds_read_b128 v[142:145], v142 offset:3072
	ds_read_b128 v[170:173], v154
	ds_read_b128 v[184:187], v154 offset:1024
	ds_read_b128 v[188:191], v154 offset:2048
	ds_read_b128 v[192:195], v154 offset:3072
	s_add_i32 m0, s14, 0xc000
	ds_read_b128 v[196:199], v183
	ds_read_b128 v[200:203], v183 offset:1024
	ds_read_b128 v[210:213], v183 offset:2048
	ds_read_b128 v[214:217], v183 offset:3072
	ds_read_b128 v[218:221], v183 offset:4096
	ds_read_b128 v[222:225], v183 offset:5120
	ds_read_b128 v[226:229], v183 offset:6144
	ds_read_b128 v[230:233], v183 offset:7168
	global_load_lds_dwordx4 v166, s[40:41]
	s_add_i32 m0, s14, 0xe000
	s_nop 0
	global_load_lds_dwordx4 v168, s[40:41]
	s_waitcnt vmcnt(8)
	s_waitcnt lgkmcnt(0)
	s_barrier
	s_setprio 1
	s_waitcnt lgkmcnt(0)
	v_mfma_f32_16x16x32_bf16 v[126:129], v[130:133], v[196:199], v[126:129]
	v_mfma_f32_16x16x32_bf16 v[122:125], v[138:141], v[196:199], v[122:125]
	v_mfma_f32_16x16x32_bf16 v[118:121], v[130:133], v[210:213], v[118:121]
	v_mfma_f32_16x16x32_bf16 v[110:113], v[138:141], v[210:213], v[110:113]
	v_mfma_f32_16x16x32_bf16 v[102:105], v[130:133], v[218:221], v[102:105]
	v_mfma_f32_16x16x32_bf16 v[94:97], v[138:141], v[218:221], v[94:97]
	v_mfma_f32_16x16x32_bf16 v[86:89], v[130:133], v[226:229], v[86:89]
	v_mfma_f32_16x16x32_bf16 v[78:81], v[138:141], v[226:229], v[78:81]
	v_mfma_f32_16x16x32_bf16 v[126:129], v[134:137], v[200:203], v[126:129]
	v_mfma_f32_16x16x32_bf16 v[122:125], v[142:145], v[200:203], v[122:125]
	v_mfma_f32_16x16x32_bf16 v[118:121], v[134:137], v[214:217], v[118:121]
	v_mfma_f32_16x16x32_bf16 v[110:113], v[142:145], v[214:217], v[110:113]
	v_mfma_f32_16x16x32_bf16 v[102:105], v[134:137], v[222:225], v[102:105]
	v_mfma_f32_16x16x32_bf16 v[94:97], v[142:145], v[222:225], v[94:97]
	v_mfma_f32_16x16x32_bf16 v[86:89], v[134:137], v[230:233], v[86:89]
	v_mfma_f32_16x16x32_bf16 v[78:81], v[142:145], v[230:233], v[78:81]
	s_setprio 0
	s_setprio 1
	v_mfma_f32_16x16x32_bf16 v[114:117], v[170:173], v[196:199], v[114:117]
	v_mfma_f32_16x16x32_bf16 v[106:109], v[188:191], v[196:199], v[106:109]
	v_mfma_f32_16x16x32_bf16 v[98:101], v[170:173], v[210:213], v[98:101]
	v_mfma_f32_16x16x32_bf16 v[90:93], v[188:191], v[210:213], v[90:93]
	v_mfma_f32_16x16x32_bf16 v[82:85], v[170:173], v[218:221], v[82:85]
	v_mfma_f32_16x16x32_bf16 v[74:77], v[188:191], v[218:221], v[74:77]
	v_mfma_f32_16x16x32_bf16 v[70:73], v[170:173], v[226:229], v[70:73]
	v_mfma_f32_16x16x32_bf16 v[66:69], v[188:191], v[226:229], v[66:69]
	v_mfma_f32_16x16x32_bf16 v[114:117], v[184:187], v[200:203], v[114:117]
	v_mfma_f32_16x16x32_bf16 v[106:109], v[192:195], v[200:203], v[106:109]
	v_mfma_f32_16x16x32_bf16 v[98:101], v[184:187], v[214:217], v[98:101]
	v_mfma_f32_16x16x32_bf16 v[90:93], v[192:195], v[214:217], v[90:93]
	v_mfma_f32_16x16x32_bf16 v[82:85], v[184:187], v[222:225], v[82:85]
	v_mfma_f32_16x16x32_bf16 v[74:77], v[192:195], v[222:225], v[74:77]
	v_mfma_f32_16x16x32_bf16 v[70:73], v[184:187], v[230:233], v[70:73]
	v_mfma_f32_16x16x32_bf16 v[66:69], v[192:195], v[230:233], v[66:69]
	s_setprio 0
	s_barrier
	s_add_i32 s52, s52, s5
	v_lshl_add_u64 v[154:155], s[42:43], 0, v[162:163]
	s_mov_b32 m0, s52
	ds_read_b128 v[196:199], v183 offset:16384
	ds_read_b128 v[200:203], v183 offset:17408
	ds_read_b128 v[210:213], v183 offset:18432
	ds_read_b128 v[214:217], v183 offset:19456
	ds_read_b128 v[218:221], v183 offset:20480
	ds_read_b128 v[222:225], v183 offset:21504
	ds_read_b128 v[226:229], v183 offset:22528
	ds_read_b128 v[230:233], v183 offset:23552
	global_load_lds_dwordx4 v[154:155], off
	s_add_i32 m0, s52, 0x2000
	s_add_u32 s52, s42, 0x80000
	v_lshl_add_u64 v[156:157], s[42:43], 0, v[158:159]
	s_addc_u32 s53, s43, 0
	s_add_i32 s54, s54, s5
	global_load_lds_dwordx4 v[156:157], off
	s_mov_b32 m0, s54
	v_lshl_add_u64 v[180:181], s[44:45], 0, v[160:161]
	global_load_lds_dwordx4 v162, s[52:53]
	s_add_i32 m0, s54, 0x2000
	s_nop 0
	global_load_lds_dwordx4 v158, s[52:53]
	v_lshl_add_u64 v[176:177], s[44:45], 0, v[164:165]
	s_mov_b32 m0, s14
	s_nop 0
	global_load_lds_dwordx4 v[176:177], off
	s_mov_b32 m0, s15
	s_nop 0
	global_load_lds_dwordx4 v[180:181], off
	s_waitcnt vmcnt(8)
	s_waitcnt lgkmcnt(0)
	s_barrier
	s_setprio 1
	s_waitcnt lgkmcnt(0)
	v_mfma_f32_16x16x32_bf16 v[62:65], v[130:133], v[196:199], v[62:65]
	v_mfma_f32_16x16x32_bf16 v[58:61], v[138:141], v[196:199], v[58:61]
	v_mfma_f32_16x16x32_bf16 v[54:57], v[130:133], v[210:213], v[54:57]
	v_mfma_f32_16x16x32_bf16 v[46:49], v[138:141], v[210:213], v[46:49]
	v_mfma_f32_16x16x32_bf16 v[38:41], v[130:133], v[218:221], v[38:41]
	v_mfma_f32_16x16x32_bf16 v[30:33], v[138:141], v[218:221], v[30:33]
	v_mfma_f32_16x16x32_bf16 v[22:25], v[130:133], v[226:229], v[22:25]
	v_mfma_f32_16x16x32_bf16 v[14:17], v[138:141], v[226:229], v[14:17]
	v_mfma_f32_16x16x32_bf16 v[62:65], v[134:137], v[200:203], v[62:65]
	v_mfma_f32_16x16x32_bf16 v[58:61], v[142:145], v[200:203], v[58:61]
	v_mfma_f32_16x16x32_bf16 v[54:57], v[134:137], v[214:217], v[54:57]
	v_mfma_f32_16x16x32_bf16 v[46:49], v[142:145], v[214:217], v[46:49]
	v_mfma_f32_16x16x32_bf16 v[38:41], v[134:137], v[222:225], v[38:41]
	v_mfma_f32_16x16x32_bf16 v[30:33], v[142:145], v[222:225], v[30:33]
	v_mfma_f32_16x16x32_bf16 v[22:25], v[134:137], v[230:233], v[22:25]
	v_mfma_f32_16x16x32_bf16 v[14:17], v[142:145], v[230:233], v[14:17]
	s_setprio 0
	s_setprio 1
	v_mfma_f32_16x16x32_bf16 v[50:53], v[170:173], v[196:199], v[50:53]
	v_mfma_f32_16x16x32_bf16 v[42:45], v[188:191], v[196:199], v[42:45]
	v_mfma_f32_16x16x32_bf16 v[34:37], v[170:173], v[210:213], v[34:37]
	v_mfma_f32_16x16x32_bf16 v[26:29], v[188:191], v[210:213], v[26:29]
	v_mfma_f32_16x16x32_bf16 v[18:21], v[170:173], v[218:221], v[18:21]
	v_mfma_f32_16x16x32_bf16 v[10:13], v[188:191], v[218:221], v[10:13]
	v_mfma_f32_16x16x32_bf16 v[6:9], v[170:173], v[226:229], v[6:9]
	v_mfma_f32_16x16x32_bf16 v[2:5], v[188:191], v[226:229], v[2:5]
	v_mfma_f32_16x16x32_bf16 v[50:53], v[184:187], v[200:203], v[50:53]
	v_mfma_f32_16x16x32_bf16 v[42:45], v[192:195], v[200:203], v[42:45]
	v_mfma_f32_16x16x32_bf16 v[34:37], v[184:187], v[214:217], v[34:37]
	v_mfma_f32_16x16x32_bf16 v[26:29], v[192:195], v[214:217], v[26:29]
	v_mfma_f32_16x16x32_bf16 v[18:21], v[184:187], v[222:225], v[18:21]
	v_mfma_f32_16x16x32_bf16 v[10:13], v[192:195], v[222:225], v[10:13]
	v_mfma_f32_16x16x32_bf16 v[6:9], v[184:187], v[230:233], v[6:9]
	v_mfma_f32_16x16x32_bf16 v[2:5], v[192:195], v[230:233], v[2:5]
	s_setprio 0
	s_barrier
	s_add_i32 s52, 0, 0x18000
	s_add_i32 s53, 0, 0x1c000
	v_add_u32_e32 v142, s52, v175
	v_add_u32_e32 v174, s53, v175
	ds_read_b128 v[130:133], v142
	ds_read_b128 v[134:137], v142 offset:1024
	ds_read_b128 v[138:141], v142 offset:2048
	ds_read_b128 v[142:145], v142 offset:3072
	ds_read_b128 v[170:173], v174
	ds_read_b128 v[184:187], v174 offset:1024
	ds_read_b128 v[188:191], v174 offset:2048
	ds_read_b128 v[192:195], v174 offset:3072
	s_add_u32 s44, s44, 0x80000
	s_addc_u32 s45, s45, 0
	s_mov_b32 m0, s16
	ds_read_b128 v[196:199], v183 offset:32768
	ds_read_b128 v[200:203], v183 offset:33792
	ds_read_b128 v[210:213], v183 offset:34816
	ds_read_b128 v[214:217], v183 offset:35840
	ds_read_b128 v[218:221], v183 offset:36864
	ds_read_b128 v[222:225], v183 offset:37888
	ds_read_b128 v[226:229], v183 offset:38912
	ds_read_b128 v[230:233], v183 offset:39936
	global_load_lds_dwordx4 v164, s[44:45]
	s_mov_b32 m0, s18
	s_nop 0
	global_load_lds_dwordx4 v160, s[44:45]
	s_waitcnt vmcnt(8)
	s_waitcnt lgkmcnt(0)
	s_barrier
	s_setprio 1
	s_waitcnt lgkmcnt(0)
	v_mfma_f32_16x16x32_bf16 v[126:129], v[130:133], v[196:199], v[126:129]
	v_mfma_f32_16x16x32_bf16 v[122:125], v[138:141], v[196:199], v[122:125]
	v_mfma_f32_16x16x32_bf16 v[118:121], v[130:133], v[210:213], v[118:121]
	v_mfma_f32_16x16x32_bf16 v[110:113], v[138:141], v[210:213], v[110:113]
	v_mfma_f32_16x16x32_bf16 v[102:105], v[130:133], v[218:221], v[102:105]
	v_mfma_f32_16x16x32_bf16 v[94:97], v[138:141], v[218:221], v[94:97]
	v_mfma_f32_16x16x32_bf16 v[86:89], v[130:133], v[226:229], v[86:89]
	v_mfma_f32_16x16x32_bf16 v[78:81], v[138:141], v[226:229], v[78:81]
	v_mfma_f32_16x16x32_bf16 v[126:129], v[134:137], v[200:203], v[126:129]
	v_mfma_f32_16x16x32_bf16 v[122:125], v[142:145], v[200:203], v[122:125]
	v_mfma_f32_16x16x32_bf16 v[118:121], v[134:137], v[214:217], v[118:121]
	v_mfma_f32_16x16x32_bf16 v[110:113], v[142:145], v[214:217], v[110:113]
	v_mfma_f32_16x16x32_bf16 v[102:105], v[134:137], v[222:225], v[102:105]
	v_mfma_f32_16x16x32_bf16 v[94:97], v[142:145], v[222:225], v[94:97]
	v_mfma_f32_16x16x32_bf16 v[86:89], v[134:137], v[230:233], v[86:89]
	v_mfma_f32_16x16x32_bf16 v[78:81], v[142:145], v[230:233], v[78:81]
	s_setprio 0
	s_setprio 1
	v_mfma_f32_16x16x32_bf16 v[114:117], v[170:173], v[196:199], v[114:117]
	v_mfma_f32_16x16x32_bf16 v[106:109], v[188:191], v[196:199], v[106:109]
	v_mfma_f32_16x16x32_bf16 v[98:101], v[170:173], v[210:213], v[98:101]
	v_mfma_f32_16x16x32_bf16 v[90:93], v[188:191], v[210:213], v[90:93]
	v_mfma_f32_16x16x32_bf16 v[82:85], v[170:173], v[218:221], v[82:85]
	v_mfma_f32_16x16x32_bf16 v[74:77], v[188:191], v[218:221], v[74:77]
	v_mfma_f32_16x16x32_bf16 v[70:73], v[170:173], v[226:229], v[70:73]
	v_mfma_f32_16x16x32_bf16 v[66:69], v[188:191], v[226:229], v[66:69]
	v_mfma_f32_16x16x32_bf16 v[114:117], v[184:187], v[200:203], v[114:117]
	v_mfma_f32_16x16x32_bf16 v[106:109], v[192:195], v[200:203], v[106:109]
	v_mfma_f32_16x16x32_bf16 v[98:101], v[184:187], v[214:217], v[98:101]
	v_mfma_f32_16x16x32_bf16 v[90:93], v[192:195], v[214:217], v[90:93]
	v_mfma_f32_16x16x32_bf16 v[82:85], v[184:187], v[222:225], v[82:85]
	v_mfma_f32_16x16x32_bf16 v[74:77], v[192:195], v[222:225], v[74:77]
	v_mfma_f32_16x16x32_bf16 v[70:73], v[184:187], v[230:233], v[70:73]
	v_mfma_f32_16x16x32_bf16 v[66:69], v[192:195], v[230:233], v[66:69]
	s_setprio 0
	s_barrier
	s_add_i32 s44, s52, s5
	v_lshl_add_u64 v[154:155], v[154:155], 0, s[34:35]
	s_mov_b32 m0, s44
	ds_read_b128 v[196:199], v183 offset:49152
	ds_read_b128 v[200:203], v183 offset:50176
	ds_read_b128 v[210:213], v183 offset:51200
	ds_read_b128 v[214:217], v183 offset:52224
	ds_read_b128 v[218:221], v183 offset:53248
	ds_read_b128 v[222:225], v183 offset:54272
	ds_read_b128 v[226:229], v183 offset:55296
	ds_read_b128 v[230:233], v183 offset:56320
	global_load_lds_dwordx4 v[154:155], off
	s_add_i32 m0, s44, 0x2000
	s_add_u32 s42, s42, 0x80080
	v_lshl_add_u64 v[154:155], v[156:157], 0, s[34:35]
	s_addc_u32 s43, s43, 0
	s_add_i32 s44, s53, s5
	global_load_lds_dwordx4 v[154:155], off
	s_mov_b32 m0, s44
	s_nop 0
	global_load_lds_dwordx4 v162, s[42:43]
	s_add_i32 m0, s44, 0x2000
	s_nop 0
	global_load_lds_dwordx4 v158, s[42:43]
	v_lshl_add_u64 v[154:155], v[176:177], 0, s[34:35]
	s_mov_b32 m0, s19
	s_nop 0
	global_load_lds_dwordx4 v[154:155], off
	v_lshl_add_u64 v[154:155], v[180:181], 0, s[34:35]
	s_mov_b32 m0, s25
	s_nop 0
	global_load_lds_dwordx4 v[154:155], off
	s_waitcnt vmcnt(8)
	s_waitcnt lgkmcnt(0)
	s_barrier
	s_setprio 1
	s_waitcnt lgkmcnt(0)
	v_mfma_f32_16x16x32_bf16 v[62:65], v[130:133], v[196:199], v[62:65]
	v_mfma_f32_16x16x32_bf16 v[58:61], v[138:141], v[196:199], v[58:61]
	v_mfma_f32_16x16x32_bf16 v[54:57], v[130:133], v[210:213], v[54:57]
	v_mfma_f32_16x16x32_bf16 v[46:49], v[138:141], v[210:213], v[46:49]
	v_mfma_f32_16x16x32_bf16 v[38:41], v[130:133], v[218:221], v[38:41]
	v_mfma_f32_16x16x32_bf16 v[30:33], v[138:141], v[218:221], v[30:33]
	v_mfma_f32_16x16x32_bf16 v[22:25], v[130:133], v[226:229], v[22:25]
	v_mfma_f32_16x16x32_bf16 v[14:17], v[138:141], v[226:229], v[14:17]
	v_mfma_f32_16x16x32_bf16 v[62:65], v[134:137], v[200:203], v[62:65]
	v_mfma_f32_16x16x32_bf16 v[58:61], v[142:145], v[200:203], v[58:61]
	v_mfma_f32_16x16x32_bf16 v[54:57], v[134:137], v[214:217], v[54:57]
	v_mfma_f32_16x16x32_bf16 v[46:49], v[142:145], v[214:217], v[46:49]
	v_mfma_f32_16x16x32_bf16 v[38:41], v[134:137], v[222:225], v[38:41]
	v_mfma_f32_16x16x32_bf16 v[30:33], v[142:145], v[222:225], v[30:33]
	v_mfma_f32_16x16x32_bf16 v[22:25], v[134:137], v[230:233], v[22:25]
	v_mfma_f32_16x16x32_bf16 v[14:17], v[142:145], v[230:233], v[14:17]
	s_setprio 0
	s_setprio 1
	v_mfma_f32_16x16x32_bf16 v[50:53], v[170:173], v[196:199], v[50:53]
	v_mfma_f32_16x16x32_bf16 v[42:45], v[188:191], v[196:199], v[42:45]
	v_mfma_f32_16x16x32_bf16 v[34:37], v[170:173], v[210:213], v[34:37]
	v_mfma_f32_16x16x32_bf16 v[26:29], v[188:191], v[210:213], v[26:29]
	v_mfma_f32_16x16x32_bf16 v[18:21], v[170:173], v[218:221], v[18:21]
	v_mfma_f32_16x16x32_bf16 v[10:13], v[188:191], v[218:221], v[10:13]
	v_mfma_f32_16x16x32_bf16 v[6:9], v[170:173], v[226:229], v[6:9]
	v_mfma_f32_16x16x32_bf16 v[2:5], v[188:191], v[226:229], v[2:5]
	v_mfma_f32_16x16x32_bf16 v[50:53], v[184:187], v[200:203], v[50:53]
	v_mfma_f32_16x16x32_bf16 v[42:45], v[192:195], v[200:203], v[42:45]
	v_mfma_f32_16x16x32_bf16 v[34:37], v[184:187], v[214:217], v[34:37]
	v_mfma_f32_16x16x32_bf16 v[26:29], v[192:195], v[214:217], v[26:29]
	v_mfma_f32_16x16x32_bf16 v[18:21], v[184:187], v[222:225], v[18:21]
	v_mfma_f32_16x16x32_bf16 v[10:13], v[192:195], v[222:225], v[10:13]
	v_mfma_f32_16x16x32_bf16 v[6:9], v[184:187], v[230:233], v[6:9]
	v_mfma_f32_16x16x32_bf16 v[2:5], v[192:195], v[230:233], v[2:5]
	s_setprio 0
	s_barrier
	s_add_i32 s51, s51, 2
	s_add_u32 s40, s40, 0x100
	s_addc_u32 s41, s41, 0
	s_add_u32 s49, s49, 0x100
	s_addc_u32 s50, s50, 0
	s_cmp_gt_u32 s51, 29
	s_cbranch_scc0 .LBB0_169
	s_and_b64 vcc, exec, s[8:9]
	s_cbranch_vccz .LBB0_172
	s_barrier

.LBB0_516:
	s_add_u32 s46, s44, 0xfff80080
	s_addc_u32 s47, s45, -1
	s_add_i32 s58, 0, 0x10000
	s_cmp_eq_u32 s57, 28
	s_cselect_b32 s49, s21, s47
	s_cselect_b32 s48, s50, s46
	s_cselect_b32 s47, s13, s56
	s_cselect_b32 s46, s51, s55
	s_add_i32 s60, 0, 0x14000
	v_add_u32_e32 v102, s58, v172
	v_add_u32_e32 v175, s60, v172
	ds_read_b128 v[82:85], v102
	ds_read_b128 v[86:89], v102 offset:1024
	ds_read_b128 v[98:101], v102 offset:2048
	ds_read_b128 v[102:105], v102 offset:3072
	ds_read_b128 v[154:157], v175
	ds_read_b128 v[168:171], v175 offset:1024
	ds_read_b128 v[176:179], v175 offset:2048
	ds_read_b128 v[180:183], v175 offset:3072
	s_add_i32 m0, s14, 0xc000
	ds_read_b128 v[184:187], v174
	ds_read_b128 v[188:191], v174 offset:1024
	ds_read_b128 v[192:195], v174 offset:2048
	ds_read_b128 v[196:199], v174 offset:3072
	ds_read_b128 v[200:203], v174 offset:4096
	ds_read_b128 v[210:213], v174 offset:5120
	ds_read_b128 v[214:217], v174 offset:6144
	ds_read_b128 v[218:221], v174 offset:7168
	global_load_lds_dwordx4 v164, s[44:45]
	s_add_i32 m0, s14, 0xe000
	s_nop 0
	global_load_lds_dwordx4 v166, s[44:45]
	s_waitcnt vmcnt(8)
	s_waitcnt lgkmcnt(0)
	s_barrier
	s_setprio 1
	s_waitcnt lgkmcnt(0)
	v_mfma_f32_16x16x32_bf16 v[142:145], v[82:85], v[184:187], v[142:145]
	v_mfma_f32_16x16x32_bf16 v[138:141], v[98:101], v[184:187], v[138:141]
	v_mfma_f32_16x16x32_bf16 v[126:129], v[82:85], v[192:195], v[126:129]
	v_mfma_f32_16x16x32_bf16 v[122:125], v[98:101], v[192:195], v[122:125]
	v_mfma_f32_16x16x32_bf16 v[110:113], v[82:85], v[200:203], v[110:113]
	v_mfma_f32_16x16x32_bf16 v[106:109], v[98:101], v[200:203], v[106:109]
	v_mfma_f32_16x16x32_bf16 v[78:81], v[82:85], v[214:217], v[78:81]
	v_mfma_f32_16x16x32_bf16 v[74:77], v[98:101], v[214:217], v[74:77]
	v_mfma_f32_16x16x32_bf16 v[142:145], v[86:89], v[188:191], v[142:145]
	v_mfma_f32_16x16x32_bf16 v[138:141], v[102:105], v[188:191], v[138:141]
	v_mfma_f32_16x16x32_bf16 v[126:129], v[86:89], v[196:199], v[126:129]
	v_mfma_f32_16x16x32_bf16 v[122:125], v[102:105], v[196:199], v[122:125]
	v_mfma_f32_16x16x32_bf16 v[110:113], v[86:89], v[210:213], v[110:113]
	v_mfma_f32_16x16x32_bf16 v[106:109], v[102:105], v[210:213], v[106:109]
	v_mfma_f32_16x16x32_bf16 v[78:81], v[86:89], v[218:221], v[78:81]
	v_mfma_f32_16x16x32_bf16 v[74:77], v[102:105], v[218:221], v[74:77]
	s_setprio 0
	s_setprio 1
	v_mfma_f32_16x16x32_bf16 v[134:137], v[154:157], v[184:187], v[134:137]
	v_mfma_f32_16x16x32_bf16 v[130:133], v[176:179], v[184:187], v[130:133]
	v_mfma_f32_16x16x32_bf16 v[118:121], v[154:157], v[192:195], v[118:121]
	v_mfma_f32_16x16x32_bf16 v[114:117], v[176:179], v[192:195], v[114:117]
	v_mfma_f32_16x16x32_bf16 v[94:97], v[154:157], v[200:203], v[94:97]
	v_mfma_f32_16x16x32_bf16 v[90:93], v[176:179], v[200:203], v[90:93]
	v_mfma_f32_16x16x32_bf16 v[70:73], v[154:157], v[214:217], v[70:73]
	v_mfma_f32_16x16x32_bf16 v[66:69], v[176:179], v[214:217], v[66:69]
	v_mfma_f32_16x16x32_bf16 v[134:137], v[168:171], v[188:191], v[134:137]
	v_mfma_f32_16x16x32_bf16 v[130:133], v[180:183], v[188:191], v[130:133]
	v_mfma_f32_16x16x32_bf16 v[118:121], v[168:171], v[196:199], v[118:121]
	v_mfma_f32_16x16x32_bf16 v[114:117], v[180:183], v[196:199], v[114:117]
	v_mfma_f32_16x16x32_bf16 v[94:97], v[168:171], v[210:213], v[94:97]
	v_mfma_f32_16x16x32_bf16 v[90:93], v[180:183], v[210:213], v[90:93]
	v_mfma_f32_16x16x32_bf16 v[70:73], v[168:171], v[218:221], v[70:73]
	v_mfma_f32_16x16x32_bf16 v[66:69], v[180:183], v[218:221], v[66:69]
	s_setprio 0
	s_barrier
	s_add_i32 s58, s58, s5
	v_lshl_add_u64 v[222:223], s[46:47], 0, v[0:1]
	s_mov_b32 m0, s58
	ds_read_b128 v[184:187], v174 offset:16384
	ds_read_b128 v[188:191], v174 offset:17408
	ds_read_b128 v[192:195], v174 offset:18432
	ds_read_b128 v[196:199], v174 offset:19456
	ds_read_b128 v[200:203], v174 offset:20480
	ds_read_b128 v[210:213], v174 offset:21504
	ds_read_b128 v[214:217], v174 offset:22528
	ds_read_b128 v[218:221], v174 offset:23552
	global_load_lds_dwordx4 v[222:223], off
	s_add_i32 m0, s58, 0x2000
	s_add_u32 s58, s46, 0x80000
	v_lshl_add_u64 v[224:225], s[46:47], 0, v[158:159]
	s_addc_u32 s59, s47, 0
	s_add_i32 s60, s60, s5
	global_load_lds_dwordx4 v[224:225], off
	s_mov_b32 m0, s60
	v_lshl_add_u64 v[228:229], s[48:49], 0, v[160:161]
	global_load_lds_dwordx4 v0, s[58:59]
	s_add_i32 m0, s60, 0x2000
	s_nop 0
	global_load_lds_dwordx4 v158, s[58:59]
	v_lshl_add_u64 v[226:227], s[48:49], 0, v[162:163]
	s_mov_b32 m0, s14
	s_nop 0
	global_load_lds_dwordx4 v[226:227], off
	s_mov_b32 m0, s15
	s_nop 0
	global_load_lds_dwordx4 v[228:229], off
	s_waitcnt vmcnt(8)
	s_waitcnt lgkmcnt(0)
	s_barrier
	s_setprio 1
	s_waitcnt lgkmcnt(0)
	v_mfma_f32_16x16x32_bf16 v[62:65], v[82:85], v[184:187], v[62:65]
	v_mfma_f32_16x16x32_bf16 v[58:61], v[98:101], v[184:187], v[58:61]
	v_mfma_f32_16x16x32_bf16 v[46:49], v[82:85], v[192:195], v[46:49]
	v_mfma_f32_16x16x32_bf16 v[42:45], v[98:101], v[192:195], v[42:45]
	v_mfma_f32_16x16x32_bf16 v[30:33], v[82:85], v[200:203], v[30:33]
	v_mfma_f32_16x16x32_bf16 v[26:29], v[98:101], v[200:203], v[26:29]
	v_mfma_f32_16x16x32_bf16 v[14:17], v[82:85], v[214:217], v[14:17]
	v_mfma_f32_16x16x32_bf16 v[10:13], v[98:101], v[214:217], v[10:13]
	v_mfma_f32_16x16x32_bf16 v[62:65], v[86:89], v[188:191], v[62:65]
	v_mfma_f32_16x16x32_bf16 v[58:61], v[102:105], v[188:191], v[58:61]
	v_mfma_f32_16x16x32_bf16 v[46:49], v[86:89], v[196:199], v[46:49]
	v_mfma_f32_16x16x32_bf16 v[42:45], v[102:105], v[196:199], v[42:45]
	v_mfma_f32_16x16x32_bf16 v[30:33], v[86:89], v[210:213], v[30:33]
	v_mfma_f32_16x16x32_bf16 v[26:29], v[102:105], v[210:213], v[26:29]
	v_mfma_f32_16x16x32_bf16 v[14:17], v[86:89], v[218:221], v[14:17]
	v_mfma_f32_16x16x32_bf16 v[10:13], v[102:105], v[218:221], v[10:13]
	s_setprio 0
	s_setprio 1
	v_mfma_f32_16x16x32_bf16 v[54:57], v[154:157], v[184:187], v[54:57]
	v_mfma_f32_16x16x32_bf16 v[50:53], v[176:179], v[184:187], v[50:53]
	v_mfma_f32_16x16x32_bf16 v[38:41], v[154:157], v[192:195], v[38:41]
	v_mfma_f32_16x16x32_bf16 v[34:37], v[176:179], v[192:195], v[34:37]
	v_mfma_f32_16x16x32_bf16 v[22:25], v[154:157], v[200:203], v[22:25]
	v_mfma_f32_16x16x32_bf16 v[18:21], v[176:179], v[200:203], v[18:21]
	v_mfma_f32_16x16x32_bf16 v[6:9], v[154:157], v[214:217], v[6:9]
	v_mfma_f32_16x16x32_bf16 v[2:5], v[176:179], v[214:217], v[2:5]
	v_mfma_f32_16x16x32_bf16 v[54:57], v[168:171], v[188:191], v[54:57]
	v_mfma_f32_16x16x32_bf16 v[50:53], v[180:183], v[188:191], v[50:53]
	v_mfma_f32_16x16x32_bf16 v[38:41], v[168:171], v[196:199], v[38:41]
	v_mfma_f32_16x16x32_bf16 v[34:37], v[180:183], v[196:199], v[34:37]
	v_mfma_f32_16x16x32_bf16 v[22:25], v[168:171], v[210:213], v[22:25]
	v_mfma_f32_16x16x32_bf16 v[18:21], v[180:183], v[210:213], v[18:21]
	v_mfma_f32_16x16x32_bf16 v[6:9], v[168:171], v[218:221], v[6:9]
	v_mfma_f32_16x16x32_bf16 v[2:5], v[180:183], v[218:221], v[2:5]
	s_setprio 0
	s_barrier
	s_add_i32 s58, 0, 0x18000
	s_add_i32 s59, 0, 0x1c000
	v_add_u32_e32 v102, s58, v172
	v_add_u32_e32 v175, s59, v172
	ds_read_b128 v[82:85], v102
	ds_read_b128 v[86:89], v102 offset:1024
	ds_read_b128 v[98:101], v102 offset:2048
	ds_read_b128 v[102:105], v102 offset:3072
	ds_read_b128 v[154:157], v175
	ds_read_b128 v[168:171], v175 offset:1024
	ds_read_b128 v[176:179], v175 offset:2048
	ds_read_b128 v[180:183], v175 offset:3072
	s_add_u32 s48, s48, 0x80000
	s_addc_u32 s49, s49, 0
	s_mov_b32 m0, s16
	ds_read_b128 v[184:187], v174 offset:32768
	ds_read_b128 v[188:191], v174 offset:33792
	ds_read_b128 v[192:195], v174 offset:34816
	ds_read_b128 v[196:199], v174 offset:35840
	ds_read_b128 v[200:203], v174 offset:36864
	ds_read_b128 v[210:213], v174 offset:37888
	ds_read_b128 v[214:217], v174 offset:38912
	ds_read_b128 v[218:221], v174 offset:39936
	global_load_lds_dwordx4 v162, s[48:49]
	s_mov_b32 m0, s18
	s_nop 0
	global_load_lds_dwordx4 v160, s[48:49]
	s_waitcnt vmcnt(8)
	s_waitcnt lgkmcnt(0)
	s_barrier
	s_setprio 1
	s_waitcnt lgkmcnt(0)
	v_mfma_f32_16x16x32_bf16 v[142:145], v[82:85], v[184:187], v[142:145]
	v_mfma_f32_16x16x32_bf16 v[138:141], v[98:101], v[184:187], v[138:141]
	v_mfma_f32_16x16x32_bf16 v[126:129], v[82:85], v[192:195], v[126:129]
	v_mfma_f32_16x16x32_bf16 v[122:125], v[98:101], v[192:195], v[122:125]
	v_mfma_f32_16x16x32_bf16 v[110:113], v[82:85], v[200:203], v[110:113]
	v_mfma_f32_16x16x32_bf16 v[106:109], v[98:101], v[200:203], v[106:109]
	v_mfma_f32_16x16x32_bf16 v[78:81], v[82:85], v[214:217], v[78:81]
	v_mfma_f32_16x16x32_bf16 v[74:77], v[98:101], v[214:217], v[74:77]
	v_mfma_f32_16x16x32_bf16 v[142:145], v[86:89], v[188:191], v[142:145]
	v_mfma_f32_16x16x32_bf16 v[138:141], v[102:105], v[188:191], v[138:141]
	v_mfma_f32_16x16x32_bf16 v[126:129], v[86:89], v[196:199], v[126:129]
	v_mfma_f32_16x16x32_bf16 v[122:125], v[102:105], v[196:199], v[122:125]
	v_mfma_f32_16x16x32_bf16 v[110:113], v[86:89], v[210:213], v[110:113]
	v_mfma_f32_16x16x32_bf16 v[106:109], v[102:105], v[210:213], v[106:109]
	v_mfma_f32_16x16x32_bf16 v[78:81], v[86:89], v[218:221], v[78:81]
	v_mfma_f32_16x16x32_bf16 v[74:77], v[102:105], v[218:221], v[74:77]
	s_setprio 0
	s_setprio 1
	v_mfma_f32_16x16x32_bf16 v[134:137], v[154:157], v[184:187], v[134:137]
	v_mfma_f32_16x16x32_bf16 v[130:133], v[176:179], v[184:187], v[130:133]
	v_mfma_f32_16x16x32_bf16 v[118:121], v[154:157], v[192:195], v[118:121]
	v_mfma_f32_16x16x32_bf16 v[114:117], v[176:179], v[192:195], v[114:117]
	v_mfma_f32_16x16x32_bf16 v[94:97], v[154:157], v[200:203], v[94:97]
	v_mfma_f32_16x16x32_bf16 v[90:93], v[176:179], v[200:203], v[90:93]
	v_mfma_f32_16x16x32_bf16 v[70:73], v[154:157], v[214:217], v[70:73]
	v_mfma_f32_16x16x32_bf16 v[66:69], v[176:179], v[214:217], v[66:69]
	v_mfma_f32_16x16x32_bf16 v[134:137], v[168:171], v[188:191], v[134:137]
	v_mfma_f32_16x16x32_bf16 v[130:133], v[180:183], v[188:191], v[130:133]
	v_mfma_f32_16x16x32_bf16 v[118:121], v[168:171], v[196:199], v[118:121]
	v_mfma_f32_16x16x32_bf16 v[114:117], v[180:183], v[196:199], v[114:117]
	v_mfma_f32_16x16x32_bf16 v[94:97], v[168:171], v[210:213], v[94:97]
	v_mfma_f32_16x16x32_bf16 v[90:93], v[180:183], v[210:213], v[90:93]
	v_mfma_f32_16x16x32_bf16 v[70:73], v[168:171], v[218:221], v[70:73]
	v_mfma_f32_16x16x32_bf16 v[66:69], v[180:183], v[218:221], v[66:69]
	s_setprio 0
	s_barrier
	s_add_i32 s48, s58, s5
	v_lshl_add_u64 v[222:223], v[222:223], 0, s[34:35]
	s_mov_b32 m0, s48
	ds_read_b128 v[184:187], v174 offset:49152
	ds_read_b128 v[188:191], v174 offset:50176
	ds_read_b128 v[192:195], v174 offset:51200
	ds_read_b128 v[196:199], v174 offset:52224
	ds_read_b128 v[200:203], v174 offset:53248
	ds_read_b128 v[210:213], v174 offset:54272
	ds_read_b128 v[214:217], v174 offset:55296
	ds_read_b128 v[218:221], v174 offset:56320
	global_load_lds_dwordx4 v[222:223], off
	s_add_i32 m0, s48, 0x2000
	s_add_u32 s46, s46, 0x80080
	v_lshl_add_u64 v[222:223], v[224:225], 0, s[34:35]
	s_addc_u32 s47, s47, 0
	s_add_i32 s48, s59, s5
	global_load_lds_dwordx4 v[222:223], off
	s_mov_b32 m0, s48
	s_nop 0
	global_load_lds_dwordx4 v0, s[46:47]
	s_add_i32 m0, s48, 0x2000
	s_nop 0
	global_load_lds_dwordx4 v158, s[46:47]
	v_lshl_add_u64 v[222:223], v[226:227], 0, s[34:35]
	s_mov_b32 m0, s25
	s_nop 0
	global_load_lds_dwordx4 v[222:223], off
	v_lshl_add_u64 v[222:223], v[228:229], 0, s[34:35]
	s_mov_b32 m0, s33
	s_nop 0
	global_load_lds_dwordx4 v[222:223], off
	s_waitcnt vmcnt(8)
	s_waitcnt lgkmcnt(0)
	s_barrier
	s_setprio 1
	s_waitcnt lgkmcnt(0)
	v_mfma_f32_16x16x32_bf16 v[62:65], v[82:85], v[184:187], v[62:65]
	v_mfma_f32_16x16x32_bf16 v[58:61], v[98:101], v[184:187], v[58:61]
	v_mfma_f32_16x16x32_bf16 v[46:49], v[82:85], v[192:195], v[46:49]
	v_mfma_f32_16x16x32_bf16 v[42:45], v[98:101], v[192:195], v[42:45]
	v_mfma_f32_16x16x32_bf16 v[30:33], v[82:85], v[200:203], v[30:33]
	v_mfma_f32_16x16x32_bf16 v[26:29], v[98:101], v[200:203], v[26:29]
	v_mfma_f32_16x16x32_bf16 v[14:17], v[82:85], v[214:217], v[14:17]
	v_mfma_f32_16x16x32_bf16 v[10:13], v[98:101], v[214:217], v[10:13]
	v_mfma_f32_16x16x32_bf16 v[62:65], v[86:89], v[188:191], v[62:65]
	v_mfma_f32_16x16x32_bf16 v[58:61], v[102:105], v[188:191], v[58:61]
	v_mfma_f32_16x16x32_bf16 v[46:49], v[86:89], v[196:199], v[46:49]
	v_mfma_f32_16x16x32_bf16 v[42:45], v[102:105], v[196:199], v[42:45]
	v_mfma_f32_16x16x32_bf16 v[30:33], v[86:89], v[210:213], v[30:33]
	v_mfma_f32_16x16x32_bf16 v[26:29], v[102:105], v[210:213], v[26:29]
	v_mfma_f32_16x16x32_bf16 v[14:17], v[86:89], v[218:221], v[14:17]
	v_mfma_f32_16x16x32_bf16 v[10:13], v[102:105], v[218:221], v[10:13]
	s_setprio 0
	s_setprio 1
	v_mfma_f32_16x16x32_bf16 v[54:57], v[154:157], v[184:187], v[54:57]
	v_mfma_f32_16x16x32_bf16 v[50:53], v[176:179], v[184:187], v[50:53]
	v_mfma_f32_16x16x32_bf16 v[38:41], v[154:157], v[192:195], v[38:41]
	v_mfma_f32_16x16x32_bf16 v[34:37], v[176:179], v[192:195], v[34:37]
	v_mfma_f32_16x16x32_bf16 v[22:25], v[154:157], v[200:203], v[22:25]
	v_mfma_f32_16x16x32_bf16 v[18:21], v[176:179], v[200:203], v[18:21]
	v_mfma_f32_16x16x32_bf16 v[6:9], v[154:157], v[214:217], v[6:9]
	v_mfma_f32_16x16x32_bf16 v[2:5], v[176:179], v[214:217], v[2:5]
	v_mfma_f32_16x16x32_bf16 v[54:57], v[168:171], v[188:191], v[54:57]
	v_mfma_f32_16x16x32_bf16 v[50:53], v[180:183], v[188:191], v[50:53]
	v_mfma_f32_16x16x32_bf16 v[38:41], v[168:171], v[196:199], v[38:41]
	v_mfma_f32_16x16x32_bf16 v[34:37], v[180:183], v[196:199], v[34:37]
	v_mfma_f32_16x16x32_bf16 v[22:25], v[168:171], v[210:213], v[22:25]
	v_mfma_f32_16x16x32_bf16 v[18:21], v[180:183], v[210:213], v[18:21]
	v_mfma_f32_16x16x32_bf16 v[6:9], v[168:171], v[218:221], v[6:9]
	v_mfma_f32_16x16x32_bf16 v[2:5], v[180:183], v[218:221], v[2:5]
	s_setprio 0
	s_barrier
	s_add_i32 s57, s57, 2
	s_add_u32 s44, s44, 0x100
	s_addc_u32 s45, s45, 0
	s_add_u32 s55, s55, 0x100
	s_addc_u32 s56, s56, 0
	s_cmp_gt_u32 s57, 29
	s_cbranch_scc0 .LBB0_516
	s_and_b64 vcc, exec, s[10:11]
	s_cbranch_vccz .LBB0_519
	s_barrier

.LBB0_604:
	s_add_u32 s22, s6, 0xfff80080
	s_addc_u32 s23, s7, -1
	s_add_i32 s54, 0, 0x10000
	s_cmp_eq_u32 s53, 28
	s_cselect_b32 s47, s18, s23
	s_cselect_b32 s46, s19, s22
	s_cselect_b32 s23, s21, s52
	s_cselect_b32 s22, s25, s41
	s_add_i32 s56, 0, 0x14000
	v_add_u32_e32 v162, s54, v175
	v_add_u32_e32 v174, s56, v175
	ds_read_b128 v[130:133], v162
	ds_read_b128 v[134:137], v162 offset:1024
	ds_read_b128 v[154:157], v162 offset:2048
	ds_read_b128 v[162:165], v162 offset:3072
	ds_read_b128 v[166:169], v174
	ds_read_b128 v[170:173], v174 offset:1024
	ds_read_b128 v[180:183], v174 offset:2048
	ds_read_b128 v[184:187], v174 offset:3072
	s_add_i32 m0, s16, 0xc000
	ds_read_b128 v[188:191], v179
	ds_read_b128 v[192:195], v179 offset:1024
	ds_read_b128 v[196:199], v179 offset:2048
	ds_read_b128 v[200:203], v179 offset:3072
	ds_read_b128 v[210:213], v179 offset:4096
	ds_read_b128 v[214:217], v179 offset:5120
	ds_read_b128 v[218:221], v179 offset:6144
	ds_read_b128 v[222:225], v179 offset:7168
	global_load_lds_dwordx4 v158, s[6:7]
	s_add_i32 m0, s16, 0xe000
	s_nop 0
	global_load_lds_dwordx4 v160, s[6:7]
	s_waitcnt vmcnt(8)
	s_waitcnt lgkmcnt(0)
	s_barrier
	s_setprio 1
	s_waitcnt lgkmcnt(0)
	v_mfma_f32_16x16x32_bf16 v[126:129], v[130:133], v[188:191], v[126:129]
	v_mfma_f32_16x16x32_bf16 v[122:125], v[154:157], v[188:191], v[122:125]
	v_mfma_f32_16x16x32_bf16 v[110:113], v[130:133], v[196:199], v[110:113]
	v_mfma_f32_16x16x32_bf16 v[106:109], v[154:157], v[196:199], v[106:109]
	v_mfma_f32_16x16x32_bf16 v[94:97], v[130:133], v[210:213], v[94:97]
	v_mfma_f32_16x16x32_bf16 v[90:93], v[154:157], v[210:213], v[90:93]
	v_mfma_f32_16x16x32_bf16 v[78:81], v[130:133], v[218:221], v[78:81]
	v_mfma_f32_16x16x32_bf16 v[74:77], v[154:157], v[218:221], v[74:77]
	v_mfma_f32_16x16x32_bf16 v[126:129], v[134:137], v[192:195], v[126:129]
	v_mfma_f32_16x16x32_bf16 v[122:125], v[162:165], v[192:195], v[122:125]
	v_mfma_f32_16x16x32_bf16 v[110:113], v[134:137], v[200:203], v[110:113]
	v_mfma_f32_16x16x32_bf16 v[106:109], v[162:165], v[200:203], v[106:109]
	v_mfma_f32_16x16x32_bf16 v[94:97], v[134:137], v[214:217], v[94:97]
	v_mfma_f32_16x16x32_bf16 v[90:93], v[162:165], v[214:217], v[90:93]
	v_mfma_f32_16x16x32_bf16 v[78:81], v[134:137], v[222:225], v[78:81]
	v_mfma_f32_16x16x32_bf16 v[74:77], v[162:165], v[222:225], v[74:77]
	s_setprio 0
	s_setprio 1
	v_mfma_f32_16x16x32_bf16 v[118:121], v[166:169], v[188:191], v[118:121]
	v_mfma_f32_16x16x32_bf16 v[114:117], v[180:183], v[188:191], v[114:117]
	v_mfma_f32_16x16x32_bf16 v[102:105], v[166:169], v[196:199], v[102:105]
	v_mfma_f32_16x16x32_bf16 v[98:101], v[180:183], v[196:199], v[98:101]
	v_mfma_f32_16x16x32_bf16 v[86:89], v[166:169], v[210:213], v[86:89]
	v_mfma_f32_16x16x32_bf16 v[82:85], v[180:183], v[210:213], v[82:85]
	v_mfma_f32_16x16x32_bf16 v[70:73], v[166:169], v[218:221], v[70:73]
	v_mfma_f32_16x16x32_bf16 v[66:69], v[180:183], v[218:221], v[66:69]
	v_mfma_f32_16x16x32_bf16 v[118:121], v[170:173], v[192:195], v[118:121]
	v_mfma_f32_16x16x32_bf16 v[114:117], v[184:187], v[192:195], v[114:117]
	v_mfma_f32_16x16x32_bf16 v[102:105], v[170:173], v[200:203], v[102:105]
	v_mfma_f32_16x16x32_bf16 v[98:101], v[184:187], v[200:203], v[98:101]
	v_mfma_f32_16x16x32_bf16 v[86:89], v[170:173], v[214:217], v[86:89]
	v_mfma_f32_16x16x32_bf16 v[82:85], v[184:187], v[214:217], v[82:85]
	v_mfma_f32_16x16x32_bf16 v[70:73], v[170:173], v[222:225], v[70:73]
	v_mfma_f32_16x16x32_bf16 v[66:69], v[184:187], v[222:225], v[66:69]
	s_setprio 0
	s_barrier
	s_add_i32 s54, s54, s15
	v_lshl_add_u64 v[226:227], s[22:23], 0, v[142:143]
	s_mov_b32 m0, s54
	ds_read_b128 v[188:191], v179 offset:16384
	ds_read_b128 v[192:195], v179 offset:17408
	ds_read_b128 v[196:199], v179 offset:18432
	ds_read_b128 v[200:203], v179 offset:19456
	ds_read_b128 v[210:213], v179 offset:20480
	ds_read_b128 v[214:217], v179 offset:21504
	ds_read_b128 v[218:221], v179 offset:22528
	ds_read_b128 v[222:225], v179 offset:23552
	global_load_lds_dwordx4 v[226:227], off
	s_add_i32 m0, s54, 0x2000
	s_add_u32 s54, s22, 0x80000
	v_lshl_add_u64 v[228:229], s[22:23], 0, v[138:139]
	s_addc_u32 s55, s23, 0
	s_add_i32 s56, s56, s15
	global_load_lds_dwordx4 v[228:229], off
	s_mov_b32 m0, s56
	v_lshl_add_u64 v[232:233], s[46:47], 0, v[140:141]
	global_load_lds_dwordx4 v142, s[54:55]
	s_add_i32 m0, s56, 0x2000
	s_nop 0
	global_load_lds_dwordx4 v138, s[54:55]
	v_lshl_add_u64 v[230:231], s[46:47], 0, v[144:145]
	s_mov_b32 m0, s16
	s_nop 0
	global_load_lds_dwordx4 v[230:231], off
	s_mov_b32 m0, s33
	s_nop 0
	global_load_lds_dwordx4 v[232:233], off
	s_waitcnt vmcnt(8)
	s_waitcnt lgkmcnt(0)
	s_barrier
	s_setprio 1
	s_waitcnt lgkmcnt(0)
	v_mfma_f32_16x16x32_bf16 v[62:65], v[130:133], v[188:191], v[62:65]
	v_mfma_f32_16x16x32_bf16 v[58:61], v[154:157], v[188:191], v[58:61]
	v_mfma_f32_16x16x32_bf16 v[46:49], v[130:133], v[196:199], v[46:49]
	v_mfma_f32_16x16x32_bf16 v[42:45], v[154:157], v[196:199], v[42:45]
	v_mfma_f32_16x16x32_bf16 v[30:33], v[130:133], v[210:213], v[30:33]
	v_mfma_f32_16x16x32_bf16 v[26:29], v[154:157], v[210:213], v[26:29]
	v_mfma_f32_16x16x32_bf16 v[14:17], v[130:133], v[218:221], v[14:17]
	v_mfma_f32_16x16x32_bf16 v[10:13], v[154:157], v[218:221], v[10:13]
	v_mfma_f32_16x16x32_bf16 v[62:65], v[134:137], v[192:195], v[62:65]
	v_mfma_f32_16x16x32_bf16 v[58:61], v[162:165], v[192:195], v[58:61]
	v_mfma_f32_16x16x32_bf16 v[46:49], v[134:137], v[200:203], v[46:49]
	v_mfma_f32_16x16x32_bf16 v[42:45], v[162:165], v[200:203], v[42:45]
	v_mfma_f32_16x16x32_bf16 v[30:33], v[134:137], v[214:217], v[30:33]
	v_mfma_f32_16x16x32_bf16 v[26:29], v[162:165], v[214:217], v[26:29]
	v_mfma_f32_16x16x32_bf16 v[14:17], v[134:137], v[222:225], v[14:17]
	v_mfma_f32_16x16x32_bf16 v[10:13], v[162:165], v[222:225], v[10:13]
	s_setprio 0
	s_setprio 1
	v_mfma_f32_16x16x32_bf16 v[54:57], v[166:169], v[188:191], v[54:57]
	v_mfma_f32_16x16x32_bf16 v[50:53], v[180:183], v[188:191], v[50:53]
	v_mfma_f32_16x16x32_bf16 v[38:41], v[166:169], v[196:199], v[38:41]
	v_mfma_f32_16x16x32_bf16 v[34:37], v[180:183], v[196:199], v[34:37]
	v_mfma_f32_16x16x32_bf16 v[22:25], v[166:169], v[210:213], v[22:25]
	v_mfma_f32_16x16x32_bf16 v[18:21], v[180:183], v[210:213], v[18:21]
	v_mfma_f32_16x16x32_bf16 v[6:9], v[166:169], v[218:221], v[6:9]
	v_mfma_f32_16x16x32_bf16 v[2:5], v[180:183], v[218:221], v[2:5]
	v_mfma_f32_16x16x32_bf16 v[54:57], v[170:173], v[192:195], v[54:57]
	v_mfma_f32_16x16x32_bf16 v[50:53], v[184:187], v[192:195], v[50:53]
	v_mfma_f32_16x16x32_bf16 v[38:41], v[170:173], v[200:203], v[38:41]
	v_mfma_f32_16x16x32_bf16 v[34:37], v[184:187], v[200:203], v[34:37]
	v_mfma_f32_16x16x32_bf16 v[22:25], v[170:173], v[214:217], v[22:25]
	v_mfma_f32_16x16x32_bf16 v[18:21], v[184:187], v[214:217], v[18:21]
	v_mfma_f32_16x16x32_bf16 v[6:9], v[170:173], v[222:225], v[6:9]
	v_mfma_f32_16x16x32_bf16 v[2:5], v[184:187], v[222:225], v[2:5]
	s_setprio 0
	s_barrier
	s_add_i32 s54, 0, 0x18000
	s_add_i32 s55, 0, 0x1c000
	v_add_u32_e32 v162, s54, v175
	v_add_u32_e32 v174, s55, v175
	ds_read_b128 v[130:133], v162
	ds_read_b128 v[134:137], v162 offset:1024
	ds_read_b128 v[154:157], v162 offset:2048
	ds_read_b128 v[162:165], v162 offset:3072
	ds_read_b128 v[166:169], v174
	ds_read_b128 v[170:173], v174 offset:1024
	ds_read_b128 v[180:183], v174 offset:2048
	ds_read_b128 v[184:187], v174 offset:3072
	s_add_u32 s46, s46, 0x80000
	s_addc_u32 s47, s47, 0
	s_mov_b32 m0, s37
	ds_read_b128 v[188:191], v179 offset:32768
	ds_read_b128 v[192:195], v179 offset:33792
	ds_read_b128 v[196:199], v179 offset:34816
	ds_read_b128 v[200:203], v179 offset:35840
	ds_read_b128 v[210:213], v179 offset:36864
	ds_read_b128 v[214:217], v179 offset:37888
	ds_read_b128 v[218:221], v179 offset:38912
	ds_read_b128 v[222:225], v179 offset:39936
	global_load_lds_dwordx4 v144, s[46:47]
	s_mov_b32 m0, s48
	s_nop 0
	global_load_lds_dwordx4 v140, s[46:47]
	s_waitcnt vmcnt(8)
	s_waitcnt lgkmcnt(0)
	s_barrier
	s_setprio 1
	s_waitcnt lgkmcnt(0)
	v_mfma_f32_16x16x32_bf16 v[126:129], v[130:133], v[188:191], v[126:129]
	v_mfma_f32_16x16x32_bf16 v[122:125], v[154:157], v[188:191], v[122:125]
	v_mfma_f32_16x16x32_bf16 v[110:113], v[130:133], v[196:199], v[110:113]
	v_mfma_f32_16x16x32_bf16 v[106:109], v[154:157], v[196:199], v[106:109]
	v_mfma_f32_16x16x32_bf16 v[94:97], v[130:133], v[210:213], v[94:97]
	v_mfma_f32_16x16x32_bf16 v[90:93], v[154:157], v[210:213], v[90:93]
	v_mfma_f32_16x16x32_bf16 v[78:81], v[130:133], v[218:221], v[78:81]
	v_mfma_f32_16x16x32_bf16 v[74:77], v[154:157], v[218:221], v[74:77]
	v_mfma_f32_16x16x32_bf16 v[126:129], v[134:137], v[192:195], v[126:129]
	v_mfma_f32_16x16x32_bf16 v[122:125], v[162:165], v[192:195], v[122:125]
	v_mfma_f32_16x16x32_bf16 v[110:113], v[134:137], v[200:203], v[110:113]
	v_mfma_f32_16x16x32_bf16 v[106:109], v[162:165], v[200:203], v[106:109]
	v_mfma_f32_16x16x32_bf16 v[94:97], v[134:137], v[214:217], v[94:97]
	v_mfma_f32_16x16x32_bf16 v[90:93], v[162:165], v[214:217], v[90:93]
	v_mfma_f32_16x16x32_bf16 v[78:81], v[134:137], v[222:225], v[78:81]
	v_mfma_f32_16x16x32_bf16 v[74:77], v[162:165], v[222:225], v[74:77]
	s_setprio 0
	s_setprio 1
	v_mfma_f32_16x16x32_bf16 v[118:121], v[166:169], v[188:191], v[118:121]
	v_mfma_f32_16x16x32_bf16 v[114:117], v[180:183], v[188:191], v[114:117]
	v_mfma_f32_16x16x32_bf16 v[102:105], v[166:169], v[196:199], v[102:105]
	v_mfma_f32_16x16x32_bf16 v[98:101], v[180:183], v[196:199], v[98:101]
	v_mfma_f32_16x16x32_bf16 v[86:89], v[166:169], v[210:213], v[86:89]
	v_mfma_f32_16x16x32_bf16 v[82:85], v[180:183], v[210:213], v[82:85]
	v_mfma_f32_16x16x32_bf16 v[70:73], v[166:169], v[218:221], v[70:73]
	v_mfma_f32_16x16x32_bf16 v[66:69], v[180:183], v[218:221], v[66:69]
	v_mfma_f32_16x16x32_bf16 v[118:121], v[170:173], v[192:195], v[118:121]
	v_mfma_f32_16x16x32_bf16 v[114:117], v[184:187], v[192:195], v[114:117]
	v_mfma_f32_16x16x32_bf16 v[102:105], v[170:173], v[200:203], v[102:105]
	v_mfma_f32_16x16x32_bf16 v[98:101], v[184:187], v[200:203], v[98:101]
	v_mfma_f32_16x16x32_bf16 v[86:89], v[170:173], v[214:217], v[86:89]
	v_mfma_f32_16x16x32_bf16 v[82:85], v[184:187], v[214:217], v[82:85]
	v_mfma_f32_16x16x32_bf16 v[70:73], v[170:173], v[222:225], v[70:73]
	v_mfma_f32_16x16x32_bf16 v[66:69], v[184:187], v[222:225], v[66:69]
	s_setprio 0
	s_barrier
	s_add_i32 s46, s54, s15
	v_lshl_add_u64 v[226:227], v[226:227], 0, s[34:35]
	s_mov_b32 m0, s46
	ds_read_b128 v[188:191], v179 offset:49152
	ds_read_b128 v[192:195], v179 offset:50176
	ds_read_b128 v[196:199], v179 offset:51200
	ds_read_b128 v[200:203], v179 offset:52224
	ds_read_b128 v[210:213], v179 offset:53248
	ds_read_b128 v[214:217], v179 offset:54272
	ds_read_b128 v[218:221], v179 offset:55296
	ds_read_b128 v[222:225], v179 offset:56320
	global_load_lds_dwordx4 v[226:227], off
	s_add_i32 m0, s46, 0x2000
	s_add_u32 s22, s22, 0x80080
	v_lshl_add_u64 v[226:227], v[228:229], 0, s[34:35]
	s_addc_u32 s23, s23, 0
	s_add_i32 s46, s55, s15
	global_load_lds_dwordx4 v[226:227], off
	s_mov_b32 m0, s46
	s_nop 0
	global_load_lds_dwordx4 v142, s[22:23]
	s_add_i32 m0, s46, 0x2000
	s_nop 0
	global_load_lds_dwordx4 v138, s[22:23]
	v_lshl_add_u64 v[226:227], v[230:231], 0, s[34:35]
	s_mov_b32 m0, s49
	s_nop 0
	global_load_lds_dwordx4 v[226:227], off
	v_lshl_add_u64 v[226:227], v[232:233], 0, s[34:35]
	s_mov_b32 m0, s50
	s_nop 0
	global_load_lds_dwordx4 v[226:227], off
	s_waitcnt vmcnt(8)
	s_waitcnt lgkmcnt(0)
	s_barrier
	s_setprio 1
	s_waitcnt lgkmcnt(0)
	v_mfma_f32_16x16x32_bf16 v[62:65], v[130:133], v[188:191], v[62:65]
	v_mfma_f32_16x16x32_bf16 v[58:61], v[154:157], v[188:191], v[58:61]
	v_mfma_f32_16x16x32_bf16 v[46:49], v[130:133], v[196:199], v[46:49]
	v_mfma_f32_16x16x32_bf16 v[42:45], v[154:157], v[196:199], v[42:45]
	v_mfma_f32_16x16x32_bf16 v[30:33], v[130:133], v[210:213], v[30:33]
	v_mfma_f32_16x16x32_bf16 v[26:29], v[154:157], v[210:213], v[26:29]
	v_mfma_f32_16x16x32_bf16 v[14:17], v[130:133], v[218:221], v[14:17]
	v_mfma_f32_16x16x32_bf16 v[10:13], v[154:157], v[218:221], v[10:13]
	v_mfma_f32_16x16x32_bf16 v[62:65], v[134:137], v[192:195], v[62:65]
	v_mfma_f32_16x16x32_bf16 v[58:61], v[162:165], v[192:195], v[58:61]
	v_mfma_f32_16x16x32_bf16 v[46:49], v[134:137], v[200:203], v[46:49]
	v_mfma_f32_16x16x32_bf16 v[42:45], v[162:165], v[200:203], v[42:45]
	v_mfma_f32_16x16x32_bf16 v[30:33], v[134:137], v[214:217], v[30:33]
	v_mfma_f32_16x16x32_bf16 v[26:29], v[162:165], v[214:217], v[26:29]
	v_mfma_f32_16x16x32_bf16 v[14:17], v[134:137], v[222:225], v[14:17]
	v_mfma_f32_16x16x32_bf16 v[10:13], v[162:165], v[222:225], v[10:13]
	s_setprio 0
	s_setprio 1
	v_mfma_f32_16x16x32_bf16 v[54:57], v[166:169], v[188:191], v[54:57]
	v_mfma_f32_16x16x32_bf16 v[50:53], v[180:183], v[188:191], v[50:53]
	v_mfma_f32_16x16x32_bf16 v[38:41], v[166:169], v[196:199], v[38:41]
	v_mfma_f32_16x16x32_bf16 v[34:37], v[180:183], v[196:199], v[34:37]
	v_mfma_f32_16x16x32_bf16 v[22:25], v[166:169], v[210:213], v[22:25]
	v_mfma_f32_16x16x32_bf16 v[18:21], v[180:183], v[210:213], v[18:21]
	v_mfma_f32_16x16x32_bf16 v[6:9], v[166:169], v[218:221], v[6:9]
	v_mfma_f32_16x16x32_bf16 v[2:5], v[180:183], v[218:221], v[2:5]
	v_mfma_f32_16x16x32_bf16 v[54:57], v[170:173], v[192:195], v[54:57]
	v_mfma_f32_16x16x32_bf16 v[50:53], v[184:187], v[192:195], v[50:53]
	v_mfma_f32_16x16x32_bf16 v[38:41], v[170:173], v[200:203], v[38:41]
	v_mfma_f32_16x16x32_bf16 v[34:37], v[184:187], v[200:203], v[34:37]
	v_mfma_f32_16x16x32_bf16 v[22:25], v[170:173], v[214:217], v[22:25]
	v_mfma_f32_16x16x32_bf16 v[18:21], v[184:187], v[214:217], v[18:21]
	v_mfma_f32_16x16x32_bf16 v[6:9], v[170:173], v[222:225], v[6:9]
	v_mfma_f32_16x16x32_bf16 v[2:5], v[184:187], v[222:225], v[2:5]
	s_setprio 0
	s_barrier
	s_add_i32 s53, s53, 2
	s_add_u32 s6, s6, 0x100
	s_addc_u32 s7, s7, 0
	s_add_u32 s41, s41, 0x100
	s_addc_u32 s52, s52, 0
	s_cmp_gt_u32 s53, 29
	s_cbranch_scc0 .LBB0_604
	s_and_b64 vcc, exec, s[12:13]
	s_cbranch_vccz .LBB0_607
	s_barrier

.LBB0_728:
	s_add_u32 s42, s22, 0x100
	s_addc_u32 s43, s23, 0
	s_add_i32 s50, 0, 0x10000
	s_cmpk_eq_i32 s25, 0x54
	s_cselect_b32 s49, s21, s43
	s_cselect_b32 s48, s20, s42
	s_cselect_b32 s47, s45, s19
	s_cselect_b32 s46, s44, s18
	s_add_i32 s51, 0, 0x14000
	v_add_u32_e32 v54, s50, v176
	v_add_u32_e32 v179, s51, v176
	ds_read_b128 v[42:45], v54
	ds_read_b128 v[46:49], v54 offset:1024
	ds_read_b128 v[50:53], v54 offset:2048
	ds_read_b128 v[54:57], v54 offset:3072
	ds_read_b128 v[154:157], v179
	ds_read_b128 v[168:171], v179 offset:1024
	ds_read_b128 v[172:175], v179 offset:2048
	ds_read_b128 v[180:183], v179 offset:3072
	s_add_i32 m0, s33, 0xc000
	ds_read_b128 v[184:187], v178
	ds_read_b128 v[188:191], v178 offset:1024
	ds_read_b128 v[192:195], v178 offset:2048
	ds_read_b128 v[196:199], v178 offset:3072
	ds_read_b128 v[200:203], v178 offset:4096
	ds_read_b128 v[210:213], v178 offset:5120
	ds_read_b128 v[214:217], v178 offset:6144
	ds_read_b128 v[218:221], v178 offset:7168
	global_load_lds_dwordx4 v164, s[22:23]
	s_add_i32 m0, s33, 0xe000
	s_nop 0
	global_load_lds_dwordx4 v166, s[22:23]
	s_waitcnt vmcnt(8)
	s_waitcnt lgkmcnt(0)
	s_barrier
	s_setprio 1
	s_waitcnt lgkmcnt(0)
	v_mfma_f32_16x16x32_bf16 v[142:145], v[42:45], v[184:187], v[142:145]
	v_mfma_f32_16x16x32_bf16 v[138:141], v[50:53], v[184:187], v[138:141]
	v_mfma_f32_16x16x32_bf16 v[126:129], v[42:45], v[192:195], v[126:129]
	v_mfma_f32_16x16x32_bf16 v[122:125], v[50:53], v[192:195], v[122:125]
	v_mfma_f32_16x16x32_bf16 v[110:113], v[42:45], v[200:203], v[110:113]
	v_mfma_f32_16x16x32_bf16 v[106:109], v[50:53], v[200:203], v[106:109]
	v_mfma_f32_16x16x32_bf16 v[94:97], v[42:45], v[214:217], v[94:97]
	v_mfma_f32_16x16x32_bf16 v[90:93], v[50:53], v[214:217], v[90:93]
	v_mfma_f32_16x16x32_bf16 v[142:145], v[46:49], v[188:191], v[142:145]
	v_mfma_f32_16x16x32_bf16 v[138:141], v[54:57], v[188:191], v[138:141]
	v_mfma_f32_16x16x32_bf16 v[126:129], v[46:49], v[196:199], v[126:129]
	v_mfma_f32_16x16x32_bf16 v[122:125], v[54:57], v[196:199], v[122:125]
	v_mfma_f32_16x16x32_bf16 v[110:113], v[46:49], v[210:213], v[110:113]
	v_mfma_f32_16x16x32_bf16 v[106:109], v[54:57], v[210:213], v[106:109]
	v_mfma_f32_16x16x32_bf16 v[94:97], v[46:49], v[218:221], v[94:97]
	v_mfma_f32_16x16x32_bf16 v[90:93], v[54:57], v[218:221], v[90:93]
	s_setprio 0
	s_setprio 1
	v_mfma_f32_16x16x32_bf16 v[134:137], v[154:157], v[184:187], v[134:137]
	v_mfma_f32_16x16x32_bf16 v[130:133], v[172:175], v[184:187], v[130:133]
	v_mfma_f32_16x16x32_bf16 v[118:121], v[154:157], v[192:195], v[118:121]
	v_mfma_f32_16x16x32_bf16 v[114:117], v[172:175], v[192:195], v[114:117]
	v_mfma_f32_16x16x32_bf16 v[102:105], v[154:157], v[200:203], v[102:105]
	v_mfma_f32_16x16x32_bf16 v[98:101], v[172:175], v[200:203], v[98:101]
	v_mfma_f32_16x16x32_bf16 v[86:89], v[154:157], v[214:217], v[86:89]
	v_mfma_f32_16x16x32_bf16 v[82:85], v[172:175], v[214:217], v[82:85]
	v_mfma_f32_16x16x32_bf16 v[134:137], v[168:171], v[188:191], v[134:137]
	v_mfma_f32_16x16x32_bf16 v[130:133], v[180:183], v[188:191], v[130:133]
	v_mfma_f32_16x16x32_bf16 v[118:121], v[168:171], v[196:199], v[118:121]
	v_mfma_f32_16x16x32_bf16 v[114:117], v[180:183], v[196:199], v[114:117]
	v_mfma_f32_16x16x32_bf16 v[102:105], v[168:171], v[210:213], v[102:105]
	v_mfma_f32_16x16x32_bf16 v[98:101], v[180:183], v[210:213], v[98:101]
	v_mfma_f32_16x16x32_bf16 v[86:89], v[168:171], v[218:221], v[86:89]
	v_mfma_f32_16x16x32_bf16 v[82:85], v[180:183], v[218:221], v[82:85]
	s_setprio 0
	s_barrier
	s_add_i32 s22, s50, s16
	v_lshl_add_u64 v[222:223], s[46:47], 0, v[0:1]
	s_mov_b32 m0, s22
	ds_read_b128 v[184:187], v178 offset:16384
	ds_read_b128 v[188:191], v178 offset:17408
	ds_read_b128 v[192:195], v178 offset:18432
	ds_read_b128 v[196:199], v178 offset:19456
	ds_read_b128 v[200:203], v178 offset:20480
	ds_read_b128 v[210:213], v178 offset:21504
	ds_read_b128 v[214:217], v178 offset:22528
	ds_read_b128 v[218:221], v178 offset:23552
	global_load_lds_dwordx4 v[222:223], off
	s_add_i32 m0, s22, 0x2000
	s_add_u32 s22, s46, 0x160000
	v_lshl_add_u64 v[224:225], s[46:47], 0, v[158:159]
	s_addc_u32 s23, s47, 0
	s_add_i32 s50, s51, s16
	global_load_lds_dwordx4 v[224:225], off
	s_mov_b32 m0, s50
	v_lshl_add_u64 v[228:229], s[48:49], 0, v[160:161]
	global_load_lds_dwordx4 v0, s[22:23]
	s_add_i32 m0, s50, 0x2000
	s_nop 0
	global_load_lds_dwordx4 v158, s[22:23]
	v_lshl_add_u64 v[226:227], s[48:49], 0, v[162:163]
	s_mov_b32 m0, s33
	s_nop 0
	global_load_lds_dwordx4 v[226:227], off
	s_mov_b32 m0, s37
	s_nop 0
	global_load_lds_dwordx4 v[228:229], off
	s_waitcnt vmcnt(8)
	s_waitcnt lgkmcnt(0)
	s_barrier
	s_setprio 1
	s_waitcnt lgkmcnt(0)
	v_mfma_f32_16x16x32_bf16 v[78:81], v[42:45], v[184:187], v[78:81]
	v_mfma_f32_16x16x32_bf16 v[74:77], v[50:53], v[184:187], v[74:77]
	v_mfma_f32_16x16x32_bf16 v[62:65], v[42:45], v[192:195], v[62:65]
	v_mfma_f32_16x16x32_bf16 v[58:61], v[50:53], v[192:195], v[58:61]
	v_mfma_f32_16x16x32_bf16 v[30:33], v[42:45], v[200:203], v[30:33]
	v_mfma_f32_16x16x32_bf16 v[26:29], v[50:53], v[200:203], v[26:29]
	v_mfma_f32_16x16x32_bf16 v[14:17], v[42:45], v[214:217], v[14:17]
	v_mfma_f32_16x16x32_bf16 v[10:13], v[50:53], v[214:217], v[10:13]
	v_mfma_f32_16x16x32_bf16 v[78:81], v[46:49], v[188:191], v[78:81]
	v_mfma_f32_16x16x32_bf16 v[74:77], v[54:57], v[188:191], v[74:77]
	v_mfma_f32_16x16x32_bf16 v[62:65], v[46:49], v[196:199], v[62:65]
	v_mfma_f32_16x16x32_bf16 v[58:61], v[54:57], v[196:199], v[58:61]
	v_mfma_f32_16x16x32_bf16 v[30:33], v[46:49], v[210:213], v[30:33]
	v_mfma_f32_16x16x32_bf16 v[26:29], v[54:57], v[210:213], v[26:29]
	v_mfma_f32_16x16x32_bf16 v[14:17], v[46:49], v[218:221], v[14:17]
	v_mfma_f32_16x16x32_bf16 v[10:13], v[54:57], v[218:221], v[10:13]
	s_setprio 0
	s_setprio 1
	v_mfma_f32_16x16x32_bf16 v[38:41], v[154:157], v[192:195], v[38:41]
	v_mfma_f32_16x16x32_bf16 v[34:37], v[172:175], v[192:195], v[34:37]
	v_mfma_f32_16x16x32_bf16 v[22:25], v[154:157], v[200:203], v[22:25]
	v_mfma_f32_16x16x32_bf16 v[18:21], v[172:175], v[200:203], v[18:21]
	v_mfma_f32_16x16x32_bf16 v[6:9], v[154:157], v[214:217], v[6:9]
	v_mfma_f32_16x16x32_bf16 v[2:5], v[172:175], v[214:217], v[2:5]
	v_mfma_f32_16x16x32_bf16 v[42:45], v[154:157], v[184:187], v[70:73]
	v_mfma_f32_16x16x32_bf16 v[46:49], v[172:175], v[184:187], v[66:69]
	v_mfma_f32_16x16x32_bf16 v[38:41], v[168:171], v[196:199], v[38:41]
	v_mfma_f32_16x16x32_bf16 v[34:37], v[180:183], v[196:199], v[34:37]
	v_mfma_f32_16x16x32_bf16 v[22:25], v[168:171], v[210:213], v[22:25]
	v_mfma_f32_16x16x32_bf16 v[18:21], v[180:183], v[210:213], v[18:21]
	v_mfma_f32_16x16x32_bf16 v[6:9], v[168:171], v[218:221], v[6:9]
	v_mfma_f32_16x16x32_bf16 v[2:5], v[180:183], v[218:221], v[2:5]
	v_mfma_f32_16x16x32_bf16 v[42:45], v[168:171], v[188:191], v[42:45]
	v_mfma_f32_16x16x32_bf16 v[46:49], v[180:183], v[188:191], v[46:49]
	s_setprio 0
	s_barrier
	s_add_i32 s50, 0, 0x18000
	s_add_i32 s51, 0, 0x1c000
	v_add_u32_e32 v70, s50, v176
	v_add_u32_e32 v179, s51, v176
	ds_read_b128 v[50:53], v70
	ds_read_b128 v[54:57], v70 offset:1024
	ds_read_b128 v[66:69], v70 offset:2048
	ds_read_b128 v[70:73], v70 offset:3072
	ds_read_b128 v[154:157], v179
	ds_read_b128 v[168:171], v179 offset:1024
	ds_read_b128 v[172:175], v179 offset:2048
	ds_read_b128 v[180:183], v179 offset:3072
	s_add_u32 s22, s48, 0x160000
	s_addc_u32 s23, s49, 0
	s_mov_b32 m0, s52
	ds_read_b128 v[184:187], v178 offset:32768
	ds_read_b128 v[188:191], v178 offset:33792
	ds_read_b128 v[192:195], v178 offset:34816
	ds_read_b128 v[196:199], v178 offset:35840
	ds_read_b128 v[200:203], v178 offset:36864
	ds_read_b128 v[210:213], v178 offset:37888
	ds_read_b128 v[214:217], v178 offset:38912
	ds_read_b128 v[218:221], v178 offset:39936
	global_load_lds_dwordx4 v162, s[22:23]
	s_mov_b32 m0, s53
	s_nop 0
	global_load_lds_dwordx4 v160, s[22:23]
	s_waitcnt vmcnt(8)
	s_waitcnt lgkmcnt(0)
	s_barrier
	s_setprio 1
	s_waitcnt lgkmcnt(0)
	v_mfma_f32_16x16x32_bf16 v[142:145], v[50:53], v[184:187], v[142:145]
	v_mfma_f32_16x16x32_bf16 v[138:141], v[66:69], v[184:187], v[138:141]
	v_mfma_f32_16x16x32_bf16 v[126:129], v[50:53], v[192:195], v[126:129]
	v_mfma_f32_16x16x32_bf16 v[122:125], v[66:69], v[192:195], v[122:125]
	v_mfma_f32_16x16x32_bf16 v[110:113], v[50:53], v[200:203], v[110:113]
	v_mfma_f32_16x16x32_bf16 v[106:109], v[66:69], v[200:203], v[106:109]
	v_mfma_f32_16x16x32_bf16 v[94:97], v[50:53], v[214:217], v[94:97]
	v_mfma_f32_16x16x32_bf16 v[90:93], v[66:69], v[214:217], v[90:93]
	v_mfma_f32_16x16x32_bf16 v[142:145], v[54:57], v[188:191], v[142:145]
	v_mfma_f32_16x16x32_bf16 v[138:141], v[70:73], v[188:191], v[138:141]
	v_mfma_f32_16x16x32_bf16 v[126:129], v[54:57], v[196:199], v[126:129]
	v_mfma_f32_16x16x32_bf16 v[122:125], v[70:73], v[196:199], v[122:125]
	v_mfma_f32_16x16x32_bf16 v[110:113], v[54:57], v[210:213], v[110:113]
	v_mfma_f32_16x16x32_bf16 v[106:109], v[70:73], v[210:213], v[106:109]
	v_mfma_f32_16x16x32_bf16 v[94:97], v[54:57], v[218:221], v[94:97]
	v_mfma_f32_16x16x32_bf16 v[90:93], v[70:73], v[218:221], v[90:93]
	s_setprio 0
	s_setprio 1
	v_mfma_f32_16x16x32_bf16 v[134:137], v[154:157], v[184:187], v[134:137]
	v_mfma_f32_16x16x32_bf16 v[130:133], v[172:175], v[184:187], v[130:133]
	v_mfma_f32_16x16x32_bf16 v[118:121], v[154:157], v[192:195], v[118:121]
	v_mfma_f32_16x16x32_bf16 v[114:117], v[172:175], v[192:195], v[114:117]
	v_mfma_f32_16x16x32_bf16 v[102:105], v[154:157], v[200:203], v[102:105]
	v_mfma_f32_16x16x32_bf16 v[98:101], v[172:175], v[200:203], v[98:101]
	v_mfma_f32_16x16x32_bf16 v[86:89], v[154:157], v[214:217], v[86:89]
	v_mfma_f32_16x16x32_bf16 v[82:85], v[172:175], v[214:217], v[82:85]
	v_mfma_f32_16x16x32_bf16 v[134:137], v[168:171], v[188:191], v[134:137]
	v_mfma_f32_16x16x32_bf16 v[130:133], v[180:183], v[188:191], v[130:133]
	v_mfma_f32_16x16x32_bf16 v[118:121], v[168:171], v[196:199], v[118:121]
	v_mfma_f32_16x16x32_bf16 v[114:117], v[180:183], v[196:199], v[114:117]
	v_mfma_f32_16x16x32_bf16 v[102:105], v[168:171], v[210:213], v[102:105]
	v_mfma_f32_16x16x32_bf16 v[98:101], v[180:183], v[210:213], v[98:101]
	v_mfma_f32_16x16x32_bf16 v[86:89], v[168:171], v[218:221], v[86:89]
	v_mfma_f32_16x16x32_bf16 v[82:85], v[180:183], v[218:221], v[82:85]
	s_setprio 0
	s_barrier
	s_add_i32 s22, s50, s16
	v_lshl_add_u64 v[222:223], v[222:223], 0, s[34:35]
	s_mov_b32 m0, s22
	ds_read_b128 v[184:187], v178 offset:49152
	ds_read_b128 v[188:191], v178 offset:50176
	ds_read_b128 v[192:195], v178 offset:51200
	ds_read_b128 v[196:199], v178 offset:52224
	ds_read_b128 v[200:203], v178 offset:53248
	ds_read_b128 v[210:213], v178 offset:54272
	ds_read_b128 v[214:217], v178 offset:55296
	ds_read_b128 v[218:221], v178 offset:56320
	global_load_lds_dwordx4 v[222:223], off
	s_add_i32 m0, s22, 0x2000
	s_add_u32 s22, s46, 0x160080
	v_lshl_add_u64 v[222:223], v[224:225], 0, s[34:35]
	s_addc_u32 s23, s47, 0
	s_add_i32 s46, s51, s16
	global_load_lds_dwordx4 v[222:223], off
	s_mov_b32 m0, s46
	s_nop 0
	global_load_lds_dwordx4 v0, s[22:23]
	s_add_i32 m0, s46, 0x2000
	s_nop 0
	global_load_lds_dwordx4 v158, s[22:23]
	v_lshl_add_u64 v[222:223], v[226:227], 0, s[34:35]
	s_mov_b32 m0, s55
	s_nop 0
	global_load_lds_dwordx4 v[222:223], off
	v_lshl_add_u64 v[222:223], v[228:229], 0, s[34:35]
	s_mov_b32 m0, s56
	s_nop 0
	global_load_lds_dwordx4 v[222:223], off
	s_waitcnt vmcnt(8)
	s_waitcnt lgkmcnt(0)
	s_barrier
	s_setprio 1
	s_waitcnt lgkmcnt(0)
	v_mfma_f32_16x16x32_bf16 v[78:81], v[50:53], v[184:187], v[78:81]
	v_mfma_f32_16x16x32_bf16 v[74:77], v[66:69], v[184:187], v[74:77]
	v_mfma_f32_16x16x32_bf16 v[62:65], v[50:53], v[192:195], v[62:65]
	v_mfma_f32_16x16x32_bf16 v[58:61], v[66:69], v[192:195], v[58:61]
	v_mfma_f32_16x16x32_bf16 v[30:33], v[50:53], v[200:203], v[30:33]
	v_mfma_f32_16x16x32_bf16 v[26:29], v[66:69], v[200:203], v[26:29]
	v_mfma_f32_16x16x32_bf16 v[14:17], v[50:53], v[214:217], v[14:17]
	v_mfma_f32_16x16x32_bf16 v[10:13], v[66:69], v[214:217], v[10:13]
	v_mfma_f32_16x16x32_bf16 v[78:81], v[54:57], v[188:191], v[78:81]
	v_mfma_f32_16x16x32_bf16 v[74:77], v[70:73], v[188:191], v[74:77]
	v_mfma_f32_16x16x32_bf16 v[62:65], v[54:57], v[196:199], v[62:65]
	v_mfma_f32_16x16x32_bf16 v[58:61], v[70:73], v[196:199], v[58:61]
	v_mfma_f32_16x16x32_bf16 v[30:33], v[54:57], v[210:213], v[30:33]
	v_mfma_f32_16x16x32_bf16 v[26:29], v[70:73], v[210:213], v[26:29]
	v_mfma_f32_16x16x32_bf16 v[14:17], v[54:57], v[218:221], v[14:17]
	v_mfma_f32_16x16x32_bf16 v[10:13], v[70:73], v[218:221], v[10:13]
	s_setprio 0
	s_setprio 1
	v_mfma_f32_16x16x32_bf16 v[42:45], v[154:157], v[184:187], v[42:45]
	v_mfma_f32_16x16x32_bf16 v[70:73], v[168:171], v[188:191], v[42:45]
	v_mfma_f32_16x16x32_bf16 v[42:45], v[172:175], v[184:187], v[46:49]
	v_mfma_f32_16x16x32_bf16 v[38:41], v[154:157], v[192:195], v[38:41]
	v_mfma_f32_16x16x32_bf16 v[34:37], v[172:175], v[192:195], v[34:37]
	v_mfma_f32_16x16x32_bf16 v[22:25], v[154:157], v[200:203], v[22:25]
	v_mfma_f32_16x16x32_bf16 v[18:21], v[172:175], v[200:203], v[18:21]
	v_mfma_f32_16x16x32_bf16 v[6:9], v[154:157], v[214:217], v[6:9]
	v_mfma_f32_16x16x32_bf16 v[2:5], v[172:175], v[214:217], v[2:5]
	v_mfma_f32_16x16x32_bf16 v[66:69], v[180:183], v[188:191], v[42:45]
	v_mfma_f32_16x16x32_bf16 v[38:41], v[168:171], v[196:199], v[38:41]
	v_mfma_f32_16x16x32_bf16 v[34:37], v[180:183], v[196:199], v[34:37]
	v_mfma_f32_16x16x32_bf16 v[22:25], v[168:171], v[210:213], v[22:25]
	v_mfma_f32_16x16x32_bf16 v[18:21], v[180:183], v[210:213], v[18:21]
	v_mfma_f32_16x16x32_bf16 v[6:9], v[168:171], v[218:221], v[6:9]
	v_mfma_f32_16x16x32_bf16 v[2:5], v[180:183], v[218:221], v[2:5]
	s_setprio 0
	s_barrier
	s_add_i32 s25, s25, 2
	s_add_u32 s18, s18, 0x100
	s_addc_u32 s19, s19, 0
	s_cmpk_gt_u32 s25, 0x55
	s_mov_b64 s[22:23], s[42:43]
	s_cbranch_scc0 .LBB0_728
	s_and_b64 vcc, exec, s[12:13]
	s_cbranch_vccz .LBB0_731
	s_barrier
